# stagger + per-XCD attention job queues with head-coherent schedule table (L2 reuse of K/V tiles)
# speedup vs baseline: 1.0057x; 1.0057x over previous
.LBB0_1575:
	s_and_saveexec_b64 s[4:5], s[6:7]
	s_cbranch_execz .LBB0_1579
	v_mov_b32_e32 v2, s57
	ds_read_b32 v0, v2 offset:4
	v_mov_b32_e32 v3, 32
	global_load_dword v3, v3, s[20:21] sc1
	s_getreg_b32 s0, hwreg(HW_REG_XCC_ID, 0, 4)
	s_and_b32 s0, s0, 7
	s_waitcnt vmcnt(0) lgkmcnt(0)
	v_readfirstlane_b32 s8, v0
	v_readfirstlane_b32 s9, v3
	s_cmpk_ge_u32 s9, 0x100
	s_cbranch_scc1 .Lqa_mem
.Lqa_loop:
	s_cmp_ge_u32 s8, 8
	s_cbranch_scc1 .Lqa_mem
	s_add_i32 s9, s0, s8
	s_and_b32 s9, s9, 7
	s_lshl_b32 s14, s9, 8
	s_addk_i32 s14, 0x100
	v_mov_b32_e32 v0, s14
	v_mov_b32_e32 v2, 1
	global_atomic_add v2, v0, v2, s[20:21] sc0
	s_waitcnt vmcnt(0)
	v_readfirstlane_b32 s15, v2
	s_cmp_lt_u32 s15, 32
	s_cbranch_scc1 .Lqa_got
	s_add_i32 s8, s8, 1
	s_branch .Lqa_loop
.Lqa_got:
	v_mov_b32_e32 v0, 32
	v_mov_b32_e32 v2, 1
	global_atomic_add v0, v2, s[20:21]
	s_lshl_b32 s9, s9, 5
	s_add_i32 s15, s15, s9
	s_branch .Lqa_pub
.Lqa_mem:
	s_mov_b32 s8, 8
	v_mov_b32_e32 v2, 1
	global_atomic_add v2, v1, v2, s[20:21] sc0
	s_waitcnt vmcnt(0)
	v_readfirstlane_b32 s15, v2
	s_addk_i32 s15, 0x100
	s_cmpk_lt_u32 s15, 0x200
	s_cbranch_scc1 .Lqa_pub
	s_movk_i32 s15, 0x200
	s_mov_b32 s8, 0
.Lqa_pub:
	v_mov_b32_e32 v0, s15
	v_mov_b32_e32 v2, s57
	v_mov_b32_e32 v3, s8
	ds_write_b32 v2, v0
	ds_write_b32 v2, v3 offset:4

.LBB0_2128:
	s_and_saveexec_b64 s[4:5], s[6:7]
	s_cbranch_execz .LBB0_2132
	v_mov_b32_e32 v2, s64
	ds_read_b32 v0, v2 offset:4
	v_mov_b32_e32 v3, 32
	global_load_dword v3, v3, s[20:21] sc1
	s_getreg_b32 s0, hwreg(HW_REG_XCC_ID, 0, 4)
	s_and_b32 s0, s0, 7
	s_waitcnt vmcnt(0) lgkmcnt(0)
	v_readfirstlane_b32 s8, v0
	v_readfirstlane_b32 s9, v3
	s_cmpk_ge_u32 s9, 0x100
	s_cbranch_scc1 .Lqb_mem

.Lqb_pub:
	v_mov_b32_e32 v0, s15
	v_mov_b32_e32 v2, s64
	v_mov_b32_e32 v3, s8
	ds_write_b32 v2, v0
	ds_write_b32 v2, v3 offset:4

_ZL10kAttnSched:
	.short	127
	.short	47
	.short	16
	.short	126
	.short	39
	.short	537
	.short	125
	.short	60
	.short	646
	.short	124
	.short	49
	.short	18
	.short	123
	.short	63
	.short	645
	.short	122
	.short	42
	.short	539
	.short	121
	.short	41
	.short	541
	.short	120
	.short	58
	.short	525
	.short	119
	.short	37
	.short	674
	.short	118
	.short	40
	.short	545
	.short	117
	.short	431
	.short	667
	.short	116
	.short	428
	.short	542
	.short	115
	.short	423
	.short	549
	.short	114
	.short	437
	.short	664
	.short	113
	.short	432
	.short	670
	.short	112
	.short	424
	.short	295
	.short	111
	.short	425
	.short	551
	.short	110
	.short	434
	.short	543
	.short	109
	.short	426
	.short	552
	.short	108
	.short	444
	.short	663
	.short	107
	.short	430
	.short	550
	.short	106
	.short	52
	.short	673
	.short	105
	.short	429
	.short	553
	.short	104
	.short	686
	.short	297
	.short	103
	.short	53
	.short	546
	.short	102
	.short	48
	.short	296
	.short	101
	.short	55
	.short	547
	.short	100
	.short	570
	.short	544
	.short	99
	.short	558
	.short	45
	.short	98
	.short	51
	.short	298
	.short	97
	.short	69
	.short	665
	.short	96
	.short	56
	.short	294
	.short	95
	.short	447
	.short	33
	.short	94
	.short	464
	.short	657
	.short	93
	.short	435
	.short	303
	.short	92
	.short	439
	.short	555
	.short	91
	.short	346
	.short	649
	.short	90
	.short	179
	.short	433
	.short	89
	.short	441
	.short	557
	.short	88
	.short	331
	.short	540
	.short	87
	.short	436
	.short	307
	.short	86
	.short	309
	.short	564
	.short	85
	.short	440
	.short	561
	.short	84
	.short	336
	.short	538
	.short	83
	.short	438
	.short	310
	.short	82
	.short	328
	.short	36
	.short	81
	.short	450
	.short	556
	.short	80
	.short	452
	.short	554
	.short	79
	.short	334
	.short	34
	.short	78
	.short	332
	.short	420
	.short	77
	.short	316
	.short	54
	.short	76
	.short	324
	.short	559
	.short	75
	.short	322
	.short	305
	.short	255
	.short	691
	.short	653
	.short	254
	.short	688
	.short	401
	.short	253
	.short	299
	.short	535
	.short	252
	.short	313
	.short	650
	.short	251
	.short	312
	.short	652
	.short	250
	.short	291
	.short	162
	.short	249
	.short	325
	.short	512
	.short	248
	.short	319
	.short	647
	.short	247
	.short	308
	.short	148
	.short	246
	.short	38
	.short	35
	.short	245
	.short	306
	.short	536
	.short	244
	.short	46
	.short	668
	.short	243
	.short	174
	.short	414
	.short	242
	.short	44
	.short	288
	.short	241
	.short	177
	.short	29
	.short	240
	.short	182
	.short	153
	.short	239
	.short	171
	.short	293
	.short	238
	.short	181
	.short	27
	.short	237
	.short	172
	.short	165
	.short	236
	.short	314
	.short	24
	.short	235
	.short	311
	.short	285
	.short	203
	.short	199
	.short	300
	.short	233
	.short	184
	.short	286
	.short	232
	.short	180
	.short	290
	.short	231
	.short	186
	.short	669
	.short	230
	.short	185
	.short	672
	.short	229
	.short	197
	.short	661
	.short	228
	.short	188
	.short	671
	.short	227
	.short	205
	.short	398
	.short	226
	.short	209
	.short	267
	.short	225
	.short	200
	.short	662
	.short	224
	.short	470
	.short	264
	.short	223
	.short	454
	.short	25
	.short	222
	.short	593
	.short	399
	.short	221
	.short	453
	.short	28
	.short	220
	.short	446
	.short	421
	.short	219
	.short	602
	.short	265
	.short	218
	.short	474
	.short	266
	.short	217
	.short	451
	.short	419
	.short	216
	.short	468
	.short	658
	.short	215
	.short	194
	.short	422
	.short	214
	.short	443
	.short	301
	.short	213
	.short	459
	.short	287
	.short	211
	.short	569
	.short	562
	.short	210
	.short	71
	.short	166
	.short	208
	.short	583
	.short	167
	.short	207
	.short	585
	.short	678
	.short	206
	.short	588
	.short	164
	.short	234
	.short	573
	.short	151
	.short	383
	.short	302
	.short	17
	.short	382
	.short	304
	.short	400
	.short	381
	.short	574
	.short	3
	.short	380
	.short	315
	.short	7
	.short	495
	.short	696
	.short	408
	.short	378
	.short	568
	.short	13
	.short	377
	.short	170
	.short	156
	.short	339
	.short	73
	.short	163
	.short	375
	.short	168
	.short	160
	.short	374
	.short	680
	.short	161
	.short	373
	.short	683
	.short	159
	.short	359
	.short	705
	.short	279
	.short	371
	.short	694
	.short	22
	.short	370
	.short	687
	.short	158
	.short	369
	.short	565
	.short	152
	.short	368
	.short	457
	.short	6
	.short	367
	.short	566
	.short	282
	.short	366
	.short	567
	.short	410
	.short	365
	.short	697
	.short	280
	.short	364
	.short	701
	.short	278
	.short	363
	.short	575
	.short	149
	.short	490
	.short	702
	.short	150
	.short	489
	.short	578
	.short	20
	.short	360
	.short	700
	.short	154
	.short	379
	.short	577
	.short	2
	.short	497
	.short	706
	.short	11
	.short	357
	.short	592
	.short	521
	.short	484
	.short	587
	.short	271
	.short	355
	.short	458
	.short	145
	.short	506
	.short	709
	.short	128
	.short	481
	.short	466
	.short	396
	.short	352
	.short	469
	.short	137
	.short	479
	.short	456
	.short	23
	.short	478
	.short	461
	.short	147
	.short	349
	.short	722
	.short	143
	.short	476
	.short	703
	.short	548
	.short	730
	.short	729
	.short	268
	.short	345
	.short	726
	.short	15
	.short	728
	.short	727
	.short	527
	.short	471
	.short	455
	.short	417
	.short	342
	.short	712
	.short	416
	.short	467
	.short	711
	.short	676
	.short	719
	.short	713
	.short	679
	.short	462
	.short	717
	.short	292
	.short	715
	.short	714
	.short	681
	.short	767
	.short	427
	.short	21
	.short	766
	.short	449
	.short	256
	.short	376
	.short	677
	.short	289
	.short	508
	.short	675
	.short	31
	.short	351
	.short	460
	.short	19
	.short	498
	.short	690
	.short	155
	.short	505
	.short	698
	.short	140
	.short	504
	.short	695
	.short	144
	.short	503
	.short	693
	.short	146
	.short	502
	.short	684
	.short	157
	.short	501
	.short	682
	.short	32
	.short	372
	.short	685
	.short	30
	.short	496
	.short	718
	.short	129
	.short	482
	.short	72
	.short	660
	.short	614
	.short	708
	.short	532
	.short	624
	.short	333
	.short	642
	.short	635
	.short	699
	.short	648
	.short	494
	.short	318
	.short	530
	.short	621
	.short	317
	.short	533
	.short	620
	.short	64
	.short	275
	.short	619
	.short	66
	.short	274
	.short	362
	.short	704
	.short	277
	.short	361
	.short	74
	.short	651
	.short	616
	.short	61
	.short	666
	.short	500
	.short	43
	.short	415
	.short	358
	.short	710
	.short	402
	.short	485
	.short	725
	.short	644
	.short	356
	.short	716
	.short	142
	.short	483
	.short	720
	.short	139
	.short	354
	.short	724
	.short	136
	.short	353
	.short	330
	.short	531
	.short	480
	.short	600
	.short	134
	.short	615
	.short	707
	.short	276
	.short	350
	.short	603
	.short	262
	.short	605
	.short	343
	.short	138
	.short	348
	.short	347
	.short	263
	.short	598
	.short	338
	.short	534
	.short	509
	.short	321
	.short	641
	.short	511
	.short	445
	.short	131
	.short	639
	.short	448
	.short	640
	.short	637
	.short	692
	.short	141
	.short	617
	.short	721
	.short	132
	.short	507
	.short	65
	.short	643
	.short	634
	.short	67
	.short	130
	.short	633
	.short	50
	.short	659
	.short	632
	.short	442
	.short	397
	.short	631
	.short	190
	.short	10
	.short	630
	.short	176
	.short	281
	.short	629
	.short	173
	.short	413
	.short	628
	.short	169
	.short	418
	.short	499
	.short	689
	.short	411
	.short	626
	.short	178
	.short	283
	.short	625
	.short	191
	.short	270
	.short	627
	.short	175
	.short	412
	.short	623
	.short	183
	.short	409
	.short	622
	.short	189
	.short	403
	.short	493
	.short	187
	.short	407
	.short	492
	.short	195
	.short	272
	.short	491
	.short	202
	.short	394
	.short	618
	.short	192
	.short	404
	.short	636
	.short	57
	.short	9
	.short	488
	.short	198
	.short	273
	.short	487
	.short	201
	.short	14
	.short	486
	.short	323
	.short	406
	.short	613
	.short	344
	.short	257
	.short	612
	.short	337
	.short	393
	.short	611
	.short	341
	.short	390
	.short	610
	.short	335
	.short	269
	.short	609
	.short	465
	.short	12
	.short	608
	.short	473
	.short	261
	.short	607
	.short	475
	.short	260
	.short	606
	.short	472
	.short	392
	.short	477
	.short	601
	.short	8
	.short	604
	.short	599
	.short	395
	.short	595
	.short	463
	.short	284
	.short	510
	.short	59
	.short	389
	.short	638
	.short	62
	.short	259
	.short	765
	.short	563
	.short	654
	.short	764
	.short	572
	.short	391
	.short	763
	.short	576
	.short	4
	.short	762
	.short	580
	.short	513
	.short	761
	.short	68
	.short	385
	.short	760
	.short	579
	.short	387
	.short	759
	.short	70
	.short	514
	.short	758
	.short	582
	.short	515
	.short	757
	.short	560
	.short	26
	.short	756
	.short	571
	.short	655
	.short	755
	.short	327
	.short	517
	.short	754
	.short	586
	.short	386
	.short	753
	.short	326
	.short	519
	.short	752
	.short	591
	.short	0
	.short	751
	.short	196
	.short	524
	.short	750
	.short	581
	.short	523
	.short	749
	.short	193
	.short	529
	.short	748
	.short	589
	.short	133
	.short	747
	.short	590
	.short	5
	.short	746
	.short	320
	.short	405
	.short	745
	.short	596
	.short	1
	.short	744
	.short	340
	.short	258
	.short	743
	.short	329
	.short	526
	.short	742
	.short	584
	.short	656
	.short	741
	.short	597
	.short	516
	.short	740
	.short	594
	.short	520
	.short	739
	.short	212
	.short	135
	.short	738
	.short	204
	.short	528
	.short	737
	.short	723
	.short	522
	.short	736
	.short	735
	.short	384
	.short	734
	.short	732
	.short	388
	.short	733
	.short	731
	.short	518
	.size	_ZL10kAttnSched, 1536

	.type	__hip_cuid_2978c3a30ac043b7,@object
